# residual GEMM epilogue: 9 x-load groups in flight instead of 7 (two more slots in dead registers)
# speedup vs baseline: 1.0003x; 1.0003x over previous
.LBB0_149:
	s_or_b64 exec, exec, s[4:5]
	v_mov_b32_e32 v72, v154
	s_lshr_b32 s5, s12, 3
	v_and_b32_e32 v136, 15, v72
	v_lshrrev_b32_e32 v73, 1, v72
	v_ashrrev_i32_e32 v72, 2, v72
	s_lshl_b32 s4, s14, 8
	s_mul_i32 s5, s5, 0x9000
	v_and_b32_e32 v152, 0xffffffc0, v72
	s_add_u32 s12, s9, s5
	v_ashrrev_i32_e32 v153, 31, v152
	s_mov_b32 s5, s52
	v_and_b32_e32 v73, 0x78, v73
	v_lshl_add_u64 v[140:141], v[152:153], 0, s[4:5]
	v_lshl_or_b32 v146, s13, 8, v73
	v_or_b32_e32 v140, v140, v136
	v_ashrrev_i32_e32 v147, 31, v146
	v_lshlrev_b64 v[144:145], 10, v[140:141]
	s_addc_u32 s13, s10, 0
	v_lshl_add_u64 v[140:141], v[144:145], 0, v[146:147]
	v_lshl_add_u64 v[148:149], v[146:147], 2, s[12:13]
	v_lshlrev_b64 v[140:141], 2, v[140:141]
	s_nop 1
	v_readfirstlane_b32 s38, v140
	v_readfirstlane_b32 s39, v141
	s_nop 1
	v_subrev_u32_e32 v139, s38, v140
	s_add_u32 s40, s0, s38
	s_addc_u32 s41, s1, s39
	s_add_u32 s42, s70, s38
	s_addc_u32 s43, s71, s39
	s_mov_b64 s[44:45], s[40:41]
	s_mov_b64 s[46:47], s[42:43]
	global_load_dwordx4 v[234:237], v[148:149], off
	global_load_dwordx4 v[238:241], v[148:149], off offset:16
	global_load_dwordx4 v[242:245], v[148:149], off offset:512
	global_load_dwordx4 v[246:249], v[148:149], off offset:528
	global_load_dwordx4 v[178:181], v139, s[40:41]
	global_load_dwordx4 v[182:185], v139, s[40:41] offset:16
	s_add_u32 s40, s40, 0x10000
	s_addc_u32 s41, s41, 0
	global_load_dwordx4 v[186:189], v139, s[40:41]
	global_load_dwordx4 v[190:193], v139, s[40:41] offset:16
	s_add_u32 s40, s40, 0x10000
	s_addc_u32 s41, s41, 0
	global_load_dwordx4 v[194:197], v139, s[40:41]
	global_load_dwordx4 v[198:201], v139, s[40:41] offset:16
	s_add_u32 s40, s40, 0x10000
	s_addc_u32 s41, s41, 0
	global_load_dwordx4 v[202:205], v139, s[40:41]
	global_load_dwordx4 v[206:209], v139, s[40:41] offset:16
	s_add_u32 s40, s40, 0x50000
	s_addc_u32 s41, s41, 0
	global_load_dwordx4 v[210:213], v139, s[40:41]
	global_load_dwordx4 v[214:217], v139, s[40:41] offset:16
	s_add_u32 s40, s40, 0x10000
	s_addc_u32 s41, s41, 0
	global_load_dwordx4 v[218:221], v139, s[40:41]
	global_load_dwordx4 v[222:225], v139, s[40:41] offset:16
	s_add_u32 s40, s40, 0x10000
	s_addc_u32 s41, s41, 0
	global_load_dwordx4 v[226:229], v139, s[40:41]
	global_load_dwordx4 v[230:233], v139, s[40:41] offset:16
	s_add_u32 s40, s40, 0x10000
	s_addc_u32 s41, s41, 0
	global_load_dwordx4 v[170:173], v139, s[40:41]
	global_load_dwordx4 v[174:177], v139, s[40:41] offset:16
	s_mov_b64 s[40:41], s[44:45]
	global_load_dwordx4 v[150:153], v139, s[40:41] offset:512
	global_load_dwordx4 v[162:165], v139, s[40:41] offset:528
	s_add_u32 s40, s40, 0x10000
	s_addc_u32 s41, s41, 0
	s_waitcnt vmcnt(16)
	v_pk_mul_f32 v[132:133], v[132:133], v[234:235]
	v_pk_mul_f32 v[134:135], v[134:135], v[236:237]
	v_pk_mul_f32 v[128:129], v[128:129], v[238:239]
	v_pk_mul_f32 v[130:131], v[130:131], v[240:241]
	v_pk_fma_f32 v[132:133], v[132:133], 0.5, v[178:179] op_sel_hi:[1,0,1]
	v_pk_fma_f32 v[134:135], v[134:135], 0.5, v[180:181] op_sel_hi:[1,0,1]
	v_pk_fma_f32 v[128:129], v[128:129], 0.5, v[182:183] op_sel_hi:[1,0,1]
	v_pk_fma_f32 v[130:131], v[130:131], 0.5, v[184:185] op_sel_hi:[1,0,1]
	global_store_dwordx4 v139, v[132:135], s[42:43]
	global_store_dwordx4 v139, v[128:131], s[42:43] offset:16
	s_add_u32 s42, s42, 0x10000
	s_addc_u32 s43, s43, 0
	global_load_dwordx4 v[178:181], v139, s[40:41] offset:512
	global_load_dwordx4 v[182:185], v139, s[40:41] offset:528
	s_add_u32 s40, s40, 0x10000
	s_addc_u32 s41, s41, 0
	s_waitcnt vmcnt(18)
	v_pk_mul_f32 v[124:125], v[124:125], v[234:235]
	v_pk_mul_f32 v[126:127], v[126:127], v[236:237]
	v_pk_mul_f32 v[120:121], v[120:121], v[238:239]
	v_pk_mul_f32 v[122:123], v[122:123], v[240:241]
	v_pk_fma_f32 v[124:125], v[124:125], 0.5, v[186:187] op_sel_hi:[1,0,1]
	v_pk_fma_f32 v[126:127], v[126:127], 0.5, v[188:189] op_sel_hi:[1,0,1]
	v_pk_fma_f32 v[120:121], v[120:121], 0.5, v[190:191] op_sel_hi:[1,0,1]
	v_pk_fma_f32 v[122:123], v[122:123], 0.5, v[192:193] op_sel_hi:[1,0,1]
	global_store_dwordx4 v139, v[124:127], s[42:43]
	global_store_dwordx4 v139, v[120:123], s[42:43] offset:16
	s_add_u32 s42, s42, 0x10000
	s_addc_u32 s43, s43, 0
	global_load_dwordx4 v[186:189], v139, s[40:41] offset:512
	global_load_dwordx4 v[190:193], v139, s[40:41] offset:528
	s_add_u32 s40, s40, 0x10000
	s_addc_u32 s41, s41, 0
	s_waitcnt vmcnt(20)
	v_pk_mul_f32 v[116:117], v[116:117], v[234:235]
	v_pk_mul_f32 v[118:119], v[118:119], v[236:237]
	v_pk_mul_f32 v[112:113], v[112:113], v[238:239]
	v_pk_mul_f32 v[114:115], v[114:115], v[240:241]
	v_pk_fma_f32 v[116:117], v[116:117], 0.5, v[194:195] op_sel_hi:[1,0,1]
	v_pk_fma_f32 v[118:119], v[118:119], 0.5, v[196:197] op_sel_hi:[1,0,1]
	v_pk_fma_f32 v[112:113], v[112:113], 0.5, v[198:199] op_sel_hi:[1,0,1]
	v_pk_fma_f32 v[114:115], v[114:115], 0.5, v[200:201] op_sel_hi:[1,0,1]
	global_store_dwordx4 v139, v[116:119], s[42:43]
	global_store_dwordx4 v139, v[112:115], s[42:43] offset:16
	s_add_u32 s42, s42, 0x10000
	s_addc_u32 s43, s43, 0
	global_load_dwordx4 v[194:197], v139, s[40:41] offset:512
	global_load_dwordx4 v[198:201], v139, s[40:41] offset:528
	s_add_u32 s40, s40, 0x50000
	s_addc_u32 s41, s41, 0
	s_waitcnt vmcnt(22)
	v_pk_mul_f32 v[108:109], v[108:109], v[234:235]
	v_pk_mul_f32 v[110:111], v[110:111], v[236:237]
	v_pk_mul_f32 v[104:105], v[104:105], v[238:239]
	v_pk_mul_f32 v[106:107], v[106:107], v[240:241]
	v_pk_fma_f32 v[108:109], v[108:109], 0.5, v[202:203] op_sel_hi:[1,0,1]
	v_pk_fma_f32 v[110:111], v[110:111], 0.5, v[204:205] op_sel_hi:[1,0,1]
	v_pk_fma_f32 v[104:105], v[104:105], 0.5, v[206:207] op_sel_hi:[1,0,1]
	v_pk_fma_f32 v[106:107], v[106:107], 0.5, v[208:209] op_sel_hi:[1,0,1]
	global_store_dwordx4 v139, v[108:111], s[42:43]
	global_store_dwordx4 v139, v[104:107], s[42:43] offset:16
	s_add_u32 s42, s42, 0x50000
	s_addc_u32 s43, s43, 0
	global_load_dwordx4 v[202:205], v139, s[40:41] offset:512
	global_load_dwordx4 v[206:209], v139, s[40:41] offset:528
	s_add_u32 s40, s40, 0x10000
	s_addc_u32 s41, s41, 0
	s_waitcnt vmcnt(24)
	v_pk_mul_f32 v[100:101], v[100:101], v[234:235]
	v_pk_mul_f32 v[102:103], v[102:103], v[236:237]
	v_pk_mul_f32 v[96:97], v[96:97], v[238:239]
	v_pk_mul_f32 v[98:99], v[98:99], v[240:241]
	v_pk_fma_f32 v[100:101], v[100:101], 0.5, v[210:211] op_sel_hi:[1,0,1]
	v_pk_fma_f32 v[102:103], v[102:103], 0.5, v[212:213] op_sel_hi:[1,0,1]
	v_pk_fma_f32 v[96:97], v[96:97], 0.5, v[214:215] op_sel_hi:[1,0,1]
	v_pk_fma_f32 v[98:99], v[98:99], 0.5, v[216:217] op_sel_hi:[1,0,1]
	global_store_dwordx4 v139, v[100:103], s[42:43]
	global_store_dwordx4 v139, v[96:99], s[42:43] offset:16
	s_add_u32 s42, s42, 0x10000
	s_addc_u32 s43, s43, 0
	global_load_dwordx4 v[210:213], v139, s[40:41] offset:512
	global_load_dwordx4 v[214:217], v139, s[40:41] offset:528
	s_add_u32 s40, s40, 0x10000
	s_addc_u32 s41, s41, 0
	s_waitcnt vmcnt(26)
	v_pk_mul_f32 v[92:93], v[92:93], v[234:235]
	v_pk_mul_f32 v[94:95], v[94:95], v[236:237]
	v_pk_mul_f32 v[88:89], v[88:89], v[238:239]
	v_pk_mul_f32 v[90:91], v[90:91], v[240:241]
	v_pk_fma_f32 v[92:93], v[92:93], 0.5, v[218:219] op_sel_hi:[1,0,1]
	v_pk_fma_f32 v[94:95], v[94:95], 0.5, v[220:221] op_sel_hi:[1,0,1]
	v_pk_fma_f32 v[88:89], v[88:89], 0.5, v[222:223] op_sel_hi:[1,0,1]
	v_pk_fma_f32 v[90:91], v[90:91], 0.5, v[224:225] op_sel_hi:[1,0,1]
	global_store_dwordx4 v139, v[92:95], s[42:43]
	global_store_dwordx4 v139, v[88:91], s[42:43] offset:16
	s_add_u32 s42, s42, 0x10000
	s_addc_u32 s43, s43, 0
	global_load_dwordx4 v[218:221], v139, s[40:41] offset:512
	global_load_dwordx4 v[222:225], v139, s[40:41] offset:528
	s_add_u32 s40, s40, 0x10000
	s_addc_u32 s41, s41, 0
	s_waitcnt vmcnt(28)
	v_pk_mul_f32 v[84:85], v[84:85], v[234:235]
	v_pk_mul_f32 v[86:87], v[86:87], v[236:237]
	v_pk_mul_f32 v[80:81], v[80:81], v[238:239]
	v_pk_mul_f32 v[82:83], v[82:83], v[240:241]
	v_pk_fma_f32 v[84:85], v[84:85], 0.5, v[226:227] op_sel_hi:[1,0,1]
	v_pk_fma_f32 v[86:87], v[86:87], 0.5, v[228:229] op_sel_hi:[1,0,1]
	v_pk_fma_f32 v[80:81], v[80:81], 0.5, v[230:231] op_sel_hi:[1,0,1]
	v_pk_fma_f32 v[82:83], v[82:83], 0.5, v[232:233] op_sel_hi:[1,0,1]
	global_store_dwordx4 v139, v[84:87], s[42:43]
	global_store_dwordx4 v139, v[80:83], s[42:43] offset:16
	s_add_u32 s42, s42, 0x10000
	s_addc_u32 s43, s43, 0
	global_load_dwordx4 v[226:229], v139, s[40:41] offset:512
	global_load_dwordx4 v[230:233], v139, s[40:41] offset:528
	s_waitcnt vmcnt(30)
	v_pk_mul_f32 v[68:69], v[68:69], v[234:235]
	v_pk_mul_f32 v[70:71], v[70:71], v[236:237]
	v_pk_mul_f32 v[64:65], v[64:65], v[238:239]
	v_pk_mul_f32 v[66:67], v[66:67], v[240:241]
	v_pk_fma_f32 v[68:69], v[68:69], 0.5, v[170:171] op_sel_hi:[1,0,1]
	v_pk_fma_f32 v[70:71], v[70:71], 0.5, v[172:173] op_sel_hi:[1,0,1]
	v_pk_fma_f32 v[64:65], v[64:65], 0.5, v[174:175] op_sel_hi:[1,0,1]
	v_pk_fma_f32 v[66:67], v[66:67], 0.5, v[176:177] op_sel_hi:[1,0,1]
	global_store_dwordx4 v139, v[68:71], s[42:43]
	global_store_dwordx4 v139, v[64:67], s[42:43] offset:16
	s_mov_b64 s[42:43], s[46:47]
	s_waitcnt vmcnt(30)
	v_pk_mul_f32 v[60:61], v[60:61], v[242:243]
	v_pk_mul_f32 v[62:63], v[62:63], v[244:245]
	v_pk_mul_f32 v[56:57], v[56:57], v[246:247]
	v_pk_mul_f32 v[58:59], v[58:59], v[248:249]
	v_pk_fma_f32 v[60:61], v[60:61], 0.5, v[150:151] op_sel_hi:[1,0,1]
	v_pk_fma_f32 v[62:63], v[62:63], 0.5, v[152:153] op_sel_hi:[1,0,1]
	v_pk_fma_f32 v[56:57], v[56:57], 0.5, v[162:163] op_sel_hi:[1,0,1]
	v_pk_fma_f32 v[58:59], v[58:59], 0.5, v[164:165] op_sel_hi:[1,0,1]
	global_store_dwordx4 v139, v[60:63], s[42:43] offset:512
	global_store_dwordx4 v139, v[56:59], s[42:43] offset:528
	s_add_u32 s42, s42, 0x10000
	s_addc_u32 s43, s43, 0
	s_waitcnt vmcnt(28)
	v_pk_mul_f32 v[52:53], v[52:53], v[242:243]
	v_pk_mul_f32 v[54:55], v[54:55], v[244:245]
	v_pk_mul_f32 v[48:49], v[48:49], v[246:247]
	v_pk_mul_f32 v[50:51], v[50:51], v[248:249]
	v_pk_fma_f32 v[52:53], v[52:53], 0.5, v[178:179] op_sel_hi:[1,0,1]
	v_pk_fma_f32 v[54:55], v[54:55], 0.5, v[180:181] op_sel_hi:[1,0,1]
	v_pk_fma_f32 v[48:49], v[48:49], 0.5, v[182:183] op_sel_hi:[1,0,1]
	v_pk_fma_f32 v[50:51], v[50:51], 0.5, v[184:185] op_sel_hi:[1,0,1]
	global_store_dwordx4 v139, v[52:55], s[42:43] offset:512
	global_store_dwordx4 v139, v[48:51], s[42:43] offset:528
	s_add_u32 s42, s42, 0x10000
	s_addc_u32 s43, s43, 0
	s_waitcnt vmcnt(26)
	v_pk_mul_f32 v[44:45], v[44:45], v[242:243]
	v_pk_mul_f32 v[46:47], v[46:47], v[244:245]
	v_pk_mul_f32 v[40:41], v[40:41], v[246:247]
	v_pk_mul_f32 v[42:43], v[42:43], v[248:249]
	v_pk_fma_f32 v[44:45], v[44:45], 0.5, v[186:187] op_sel_hi:[1,0,1]
	v_pk_fma_f32 v[46:47], v[46:47], 0.5, v[188:189] op_sel_hi:[1,0,1]
	v_pk_fma_f32 v[40:41], v[40:41], 0.5, v[190:191] op_sel_hi:[1,0,1]
	v_pk_fma_f32 v[42:43], v[42:43], 0.5, v[192:193] op_sel_hi:[1,0,1]
	global_store_dwordx4 v139, v[44:47], s[42:43] offset:512
	global_store_dwordx4 v139, v[40:43], s[42:43] offset:528
	s_add_u32 s42, s42, 0x10000
	s_addc_u32 s43, s43, 0
	s_waitcnt vmcnt(24)
	v_pk_mul_f32 v[32:33], v[32:33], v[242:243]
	v_pk_mul_f32 v[34:35], v[34:35], v[244:245]
	v_pk_mul_f32 v[24:25], v[24:25], v[246:247]
	v_pk_mul_f32 v[26:27], v[26:27], v[248:249]
	v_pk_fma_f32 v[32:33], v[32:33], 0.5, v[194:195] op_sel_hi:[1,0,1]
	v_pk_fma_f32 v[34:35], v[34:35], 0.5, v[196:197] op_sel_hi:[1,0,1]
	v_pk_fma_f32 v[24:25], v[24:25], 0.5, v[198:199] op_sel_hi:[1,0,1]
	v_pk_fma_f32 v[26:27], v[26:27], 0.5, v[200:201] op_sel_hi:[1,0,1]
	global_store_dwordx4 v139, v[32:35], s[42:43] offset:512
	global_store_dwordx4 v139, v[24:27], s[42:43] offset:528
	s_add_u32 s42, s42, 0x50000
	s_addc_u32 s43, s43, 0
	s_waitcnt vmcnt(22)
	v_pk_mul_f32 v[36:37], v[36:37], v[242:243]
	v_pk_mul_f32 v[38:39], v[38:39], v[244:245]
	v_pk_mul_f32 v[28:29], v[28:29], v[246:247]
	v_pk_mul_f32 v[30:31], v[30:31], v[248:249]
	v_pk_fma_f32 v[36:37], v[36:37], 0.5, v[202:203] op_sel_hi:[1,0,1]
	v_pk_fma_f32 v[38:39], v[38:39], 0.5, v[204:205] op_sel_hi:[1,0,1]
	v_pk_fma_f32 v[28:29], v[28:29], 0.5, v[206:207] op_sel_hi:[1,0,1]
	v_pk_fma_f32 v[30:31], v[30:31], 0.5, v[208:209] op_sel_hi:[1,0,1]
	global_store_dwordx4 v139, v[36:39], s[42:43] offset:512
	global_store_dwordx4 v139, v[28:31], s[42:43] offset:528
	s_add_u32 s42, s42, 0x10000
	s_addc_u32 s43, s43, 0
	s_waitcnt vmcnt(20)
	v_pk_mul_f32 v[20:21], v[20:21], v[242:243]
	v_pk_mul_f32 v[22:23], v[22:23], v[244:245]
	v_pk_mul_f32 v[16:17], v[16:17], v[246:247]
	v_pk_mul_f32 v[18:19], v[18:19], v[248:249]
	v_pk_fma_f32 v[20:21], v[20:21], 0.5, v[210:211] op_sel_hi:[1,0,1]
	v_pk_fma_f32 v[22:23], v[22:23], 0.5, v[212:213] op_sel_hi:[1,0,1]
	v_pk_fma_f32 v[16:17], v[16:17], 0.5, v[214:215] op_sel_hi:[1,0,1]
	v_pk_fma_f32 v[18:19], v[18:19], 0.5, v[216:217] op_sel_hi:[1,0,1]
	global_store_dwordx4 v139, v[20:23], s[42:43] offset:512
	global_store_dwordx4 v139, v[16:19], s[42:43] offset:528
	s_add_u32 s42, s42, 0x10000
	s_addc_u32 s43, s43, 0
	s_waitcnt vmcnt(18)
	v_pk_mul_f32 v[12:13], v[12:13], v[242:243]
	v_pk_mul_f32 v[14:15], v[14:15], v[244:245]
	v_pk_mul_f32 v[8:9], v[8:9], v[246:247]
	v_pk_mul_f32 v[10:11], v[10:11], v[248:249]
	v_pk_fma_f32 v[12:13], v[12:13], 0.5, v[218:219] op_sel_hi:[1,0,1]
	v_pk_fma_f32 v[14:15], v[14:15], 0.5, v[220:221] op_sel_hi:[1,0,1]
	v_pk_fma_f32 v[8:9], v[8:9], 0.5, v[222:223] op_sel_hi:[1,0,1]
	v_pk_fma_f32 v[10:11], v[10:11], 0.5, v[224:225] op_sel_hi:[1,0,1]
	global_store_dwordx4 v139, v[12:15], s[42:43] offset:512
	global_store_dwordx4 v139, v[8:11], s[42:43] offset:528
	s_add_u32 s42, s42, 0x10000
	s_addc_u32 s43, s43, 0
	s_waitcnt vmcnt(16)
	v_pk_mul_f32 v[4:5], v[4:5], v[242:243]
	v_pk_mul_f32 v[6:7], v[6:7], v[244:245]
	v_pk_mul_f32 v[0:1], v[0:1], v[246:247]
	v_pk_mul_f32 v[2:3], v[2:3], v[248:249]
	v_pk_fma_f32 v[4:5], v[4:5], 0.5, v[226:227] op_sel_hi:[1,0,1]
	v_pk_fma_f32 v[6:7], v[6:7], 0.5, v[228:229] op_sel_hi:[1,0,1]
	v_pk_fma_f32 v[0:1], v[0:1], 0.5, v[230:231] op_sel_hi:[1,0,1]
	v_pk_fma_f32 v[2:3], v[2:3], 0.5, v[232:233] op_sel_hi:[1,0,1]
	global_store_dwordx4 v139, v[4:7], s[42:43] offset:512
	global_store_dwordx4 v139, v[0:3], s[42:43] offset:528
	v_pk_mul_f32 v[200:201], v[132:133], v[132:133]
	v_pk_mul_f32 v[202:203], v[124:125], v[124:125]
	v_pk_mul_f32 v[204:205], v[116:117], v[116:117]
	v_pk_mul_f32 v[206:207], v[108:109], v[108:109]
	v_pk_mul_f32 v[208:209], v[100:101], v[100:101]
	v_pk_mul_f32 v[210:211], v[92:93], v[92:93]
	v_pk_mul_f32 v[212:213], v[84:85], v[84:85]
	v_pk_mul_f32 v[214:215], v[68:69], v[68:69]
	v_pk_fma_f32 v[200:201], v[134:135], v[134:135], v[200:201]
	v_pk_fma_f32 v[202:203], v[126:127], v[126:127], v[202:203]
	v_pk_fma_f32 v[204:205], v[118:119], v[118:119], v[204:205]
	v_pk_fma_f32 v[206:207], v[110:111], v[110:111], v[206:207]
	v_pk_fma_f32 v[208:209], v[102:103], v[102:103], v[208:209]
	v_pk_fma_f32 v[210:211], v[94:95], v[94:95], v[210:211]
	v_pk_fma_f32 v[212:213], v[86:87], v[86:87], v[212:213]
	v_pk_fma_f32 v[214:215], v[70:71], v[70:71], v[214:215]
	v_pk_fma_f32 v[200:201], v[128:129], v[128:129], v[200:201]
	v_pk_fma_f32 v[202:203], v[120:121], v[120:121], v[202:203]
	v_pk_fma_f32 v[204:205], v[112:113], v[112:113], v[204:205]
	v_pk_fma_f32 v[206:207], v[104:105], v[104:105], v[206:207]
	v_pk_fma_f32 v[208:209], v[96:97], v[96:97], v[208:209]
	v_pk_fma_f32 v[210:211], v[88:89], v[88:89], v[210:211]
	v_pk_fma_f32 v[212:213], v[80:81], v[80:81], v[212:213]
	v_pk_fma_f32 v[214:215], v[64:65], v[64:65], v[214:215]
	v_pk_fma_f32 v[200:201], v[130:131], v[130:131], v[200:201]
	v_pk_fma_f32 v[202:203], v[122:123], v[122:123], v[202:203]
	v_pk_fma_f32 v[204:205], v[114:115], v[114:115], v[204:205]
	v_pk_fma_f32 v[206:207], v[106:107], v[106:107], v[206:207]
	v_pk_fma_f32 v[208:209], v[98:99], v[98:99], v[208:209]
	v_pk_fma_f32 v[210:211], v[90:91], v[90:91], v[210:211]
	v_pk_fma_f32 v[212:213], v[82:83], v[82:83], v[212:213]
	v_pk_fma_f32 v[214:215], v[66:67], v[66:67], v[214:215]
	v_pk_fma_f32 v[200:201], v[60:61], v[60:61], v[200:201]
	v_pk_fma_f32 v[202:203], v[52:53], v[52:53], v[202:203]
	v_pk_fma_f32 v[204:205], v[44:45], v[44:45], v[204:205]
	v_pk_fma_f32 v[206:207], v[32:33], v[32:33], v[206:207]
	v_pk_fma_f32 v[208:209], v[36:37], v[36:37], v[208:209]
	v_pk_fma_f32 v[210:211], v[20:21], v[20:21], v[210:211]
	v_pk_fma_f32 v[212:213], v[12:13], v[12:13], v[212:213]
	v_pk_fma_f32 v[214:215], v[4:5], v[4:5], v[214:215]
	v_pk_fma_f32 v[200:201], v[62:63], v[62:63], v[200:201]
	v_pk_fma_f32 v[202:203], v[54:55], v[54:55], v[202:203]
	v_pk_fma_f32 v[204:205], v[46:47], v[46:47], v[204:205]
	v_pk_fma_f32 v[206:207], v[34:35], v[34:35], v[206:207]
	v_pk_fma_f32 v[208:209], v[38:39], v[38:39], v[208:209]
	v_pk_fma_f32 v[210:211], v[22:23], v[22:23], v[210:211]
	v_pk_fma_f32 v[212:213], v[14:15], v[14:15], v[212:213]
	v_pk_fma_f32 v[214:215], v[6:7], v[6:7], v[214:215]
	v_pk_fma_f32 v[200:201], v[56:57], v[56:57], v[200:201]
	v_pk_fma_f32 v[202:203], v[48:49], v[48:49], v[202:203]
	v_pk_fma_f32 v[204:205], v[40:41], v[40:41], v[204:205]
	v_pk_fma_f32 v[206:207], v[24:25], v[24:25], v[206:207]
	v_pk_fma_f32 v[208:209], v[28:29], v[28:29], v[208:209]
	v_pk_fma_f32 v[210:211], v[16:17], v[16:17], v[210:211]
	v_pk_fma_f32 v[212:213], v[8:9], v[8:9], v[212:213]
	v_pk_fma_f32 v[214:215], v[0:1], v[0:1], v[214:215]
	v_pk_fma_f32 v[200:201], v[58:59], v[58:59], v[200:201]
	v_pk_fma_f32 v[202:203], v[50:51], v[50:51], v[202:203]
	v_pk_fma_f32 v[204:205], v[42:43], v[42:43], v[204:205]
	v_pk_fma_f32 v[206:207], v[26:27], v[26:27], v[206:207]
	v_pk_fma_f32 v[208:209], v[30:31], v[30:31], v[208:209]
	v_pk_fma_f32 v[210:211], v[18:19], v[18:19], v[210:211]
	v_pk_fma_f32 v[212:213], v[10:11], v[10:11], v[212:213]
	v_pk_fma_f32 v[214:215], v[2:3], v[2:3], v[214:215]
	v_add_f32_e32 v216, v200, v201
	v_add_f32_e32 v217, v202, v203
	v_add_f32_e32 v218, v204, v205
	v_add_f32_e32 v219, v206, v207
	v_add_f32_e32 v220, v208, v209
	v_add_f32_e32 v221, v210, v211
	v_add_f32_e32 v222, v212, v213
	v_add_f32_e32 v223, v214, v215
	v_and_b32_e32 v224, 63, v154
	v_xor_b32_e32 v225, 32, v224
	v_xor_b32_e32 v224, 16, v224
	v_lshlrev_b32_e32 v224, 2, v224
	v_lshlrev_b32_e32 v225, 2, v225
	ds_bpermute_b32 v226, v224, v216
	ds_bpermute_b32 v227, v224, v217
	ds_bpermute_b32 v228, v224, v218
	ds_bpermute_b32 v229, v224, v219
	ds_bpermute_b32 v230, v224, v220
	ds_bpermute_b32 v231, v224, v221
	ds_bpermute_b32 v232, v224, v222
	ds_bpermute_b32 v233, v224, v223
	s_waitcnt lgkmcnt(0)
	v_add_f32_e32 v216, v216, v226
	v_add_f32_e32 v217, v217, v227
	v_add_f32_e32 v218, v218, v228
	v_add_f32_e32 v219, v219, v229
	v_add_f32_e32 v220, v220, v230
	v_add_f32_e32 v221, v221, v231
	v_add_f32_e32 v222, v222, v232
	v_add_f32_e32 v223, v223, v233
	ds_bpermute_b32 v226, v225, v216
	ds_bpermute_b32 v227, v225, v217
	ds_bpermute_b32 v228, v225, v218
	ds_bpermute_b32 v229, v225, v219
	ds_bpermute_b32 v230, v225, v220
	ds_bpermute_b32 v231, v225, v221
	ds_bpermute_b32 v232, v225, v222
	ds_bpermute_b32 v233, v225, v223
	s_waitcnt lgkmcnt(0)
	v_add_f32_e32 v216, v216, v226
	v_add_f32_e32 v217, v217, v227
	v_add_f32_e32 v218, v218, v228
	v_add_f32_e32 v219, v219, v229
	v_add_f32_e32 v220, v220, v230
	v_add_f32_e32 v221, v221, v231
	v_add_f32_e32 v222, v222, v232
	v_add_f32_e32 v223, v223, v233
	v_bfe_u32 v234, v154, 6, 2
	v_lshlrev_b32_e32 v234, 8, v234
	v_lshrrev_b32_e32 v235, 8, v154
	v_lshl_add_u32 v234, v235, 6, v234
	v_and_b32_e32 v235, 15, v154
	v_add_u32_e32 v234, v234, v235
	v_lshlrev_b32_e32 v234, 2, v234
	ds_write_b32 v234, v216 offset:0
	ds_write_b32 v234, v217 offset:64
	ds_write_b32 v234, v218 offset:128
	ds_write_b32 v234, v219 offset:192
	ds_write_b32 v234, v220 offset:512
	ds_write_b32 v234, v221 offset:576
	ds_write_b32 v234, v222 offset:640
	ds_write_b32 v234, v223 offset:704
	s_waitcnt lgkmcnt(0)
	s_barrier
	v_cmp_gt_u32_e32 vcc, 0x100, v154
	s_and_saveexec_b64 s[48:49], vcc
	v_lshlrev_b32_e32 v235, 2, v154
	ds_read_b32 v236, v235
	ds_read_b32 v237, v235 offset:1024
	ds_read_b32 v238, v235 offset:2048
	ds_read_b32 v239, v235 offset:3072
	s_lshl_b32 s50, s6, 3
	s_and_b32 s50, s50, 56
	s_bfe_u32 s51, s6, 0x30003
	s_or_b32 s50, s50, s51
	s_lshl_b32 s50, s50, 2
	s_lshr_b32 s51, s6, 6
	s_or_b32 s50, s50, s51
	s_lshl_b32 s50, s50, 10
	s_add_u32 s50, s50, s72
	s_addc_u32 s51, s73, 0
	s_add_u32 s50, s50, 0x19500000
	s_addc_u32 s51, s51, 0
	s_waitcnt lgkmcnt(0)
	v_add_f32_e32 v236, v236, v237
	v_add_f32_e32 v238, v238, v239
	v_add_f32_e32 v236, v236, v238
	global_store_dword v235, v236, s[50:51]
	s_mov_b64 exec, s[48:49]
	s_mov_b32 s92, s6
	v_mov_b64_e32 v[242:243], v[0:1]
	v_mov_b64_e32 v[244:245], v[2:3]
	v_mov_b64_e32 v[246:247], v[4:5]
	v_mov_b64_e32 v[248:249], v[6:7]
	s_add_i32 s6, s6, s74
	s_add_i32 s11, s11, s20
	s_cmpk_lt_i32 s6, 0x100
	s_cbranch_scc0 .LBB0_156

.LBB0_587:
	s_or_b64 exec, exec, s[4:5]
	v_mov_b32_e32 v80, v154
	s_lshl_b32 s4, s15, 8
	v_and_b32_e32 v136, 15, v80
	v_lshrrev_b32_e32 v81, 1, v80
	v_ashrrev_i32_e32 v80, 2, v80
	v_and_b32_e32 v152, 0xffffffc0, v80
	v_ashrrev_i32_e32 v153, 31, v152
	s_mov_b32 s5, s52
	s_lshr_b32 s1, s14, 3
	v_and_b32_e32 v81, 0x78, v81
	v_lshl_add_u64 v[140:141], v[152:153], 0, s[4:5]
	v_lshl_or_b32 v144, s0, 8, v81
	s_mul_i32 s1, s1, 0x9000
	v_or_b32_e32 v140, v140, v136
	s_add_u32 s0, s11, s1
	v_ashrrev_i32_e32 v145, 31, v144
	v_lshlrev_b64 v[140:141], 12, v[140:141]
	s_addc_u32 s1, s12, 0
	v_lshlrev_b64 v[150:151], 2, v[144:145]
	v_lshl_add_u64 v[170:171], s[70:71], 0, v[140:141]
	v_lshl_add_u64 v[146:147], s[0:1], 0, v[150:151]
	v_lshl_add_u64 v[148:149], v[170:171], 0, v[150:151]
	s_nop 1
	v_readfirstlane_b32 s38, v148
	v_readfirstlane_b32 s39, v149
	s_nop 1
	v_subrev_u32_e32 v139, s38, v148
	s_mov_b64 s[40:41], s[38:39]
	s_mov_b64 s[42:43], s[38:39]
	s_mov_b64 s[44:45], s[40:41]
	s_mov_b64 s[46:47], s[42:43]
	s_mov_b64 s[36:37], 0x20000
	global_load_dwordx4 v[234:237], v[146:147], off
	global_load_dwordx4 v[238:241], v[146:147], off offset:16
	global_load_dwordx4 v[242:245], v[146:147], off offset:512
	global_load_dwordx4 v[246:249], v[146:147], off offset:528
	global_load_dwordx4 v[178:181], v139, s[40:41]
	global_load_dwordx4 v[182:185], v139, s[40:41] offset:16
	s_add_u32 s40, s40, 0x10000
	s_addc_u32 s41, s41, 0
	global_load_dwordx4 v[186:189], v139, s[40:41]
	global_load_dwordx4 v[190:193], v139, s[40:41] offset:16
	s_add_u32 s40, s40, 0x10000
	s_addc_u32 s41, s41, 0
	global_load_dwordx4 v[194:197], v139, s[40:41]
	global_load_dwordx4 v[198:201], v139, s[40:41] offset:16
	s_add_u32 s40, s40, 0x10000
	s_addc_u32 s41, s41, 0
	global_load_dwordx4 v[202:205], v139, s[40:41]
	global_load_dwordx4 v[206:209], v139, s[40:41] offset:16
	s_add_u32 s40, s40, 0x50000
	s_addc_u32 s41, s41, 0
	global_load_dwordx4 v[210:213], v139, s[40:41]
	global_load_dwordx4 v[214:217], v139, s[40:41] offset:16
	s_add_u32 s40, s40, 0x10000
	s_addc_u32 s41, s41, 0
	global_load_dwordx4 v[218:221], v139, s[40:41]
	global_load_dwordx4 v[222:225], v139, s[40:41] offset:16
	s_add_u32 s40, s40, 0x10000
	s_addc_u32 s41, s41, 0
	global_load_dwordx4 v[226:229], v139, s[40:41]
	global_load_dwordx4 v[230:233], v139, s[40:41] offset:16
	s_add_u32 s40, s40, 0x10000
	s_addc_u32 s41, s41, 0
	global_load_dwordx4 v[170:173], v139, s[40:41]
	global_load_dwordx4 v[174:177], v139, s[40:41] offset:16
	s_mov_b64 s[40:41], s[44:45]
	global_load_dwordx4 v[150:153], v139, s[40:41] offset:512
	global_load_dwordx4 v[162:165], v139, s[40:41] offset:528
	s_add_u32 s40, s40, 0x10000
	s_addc_u32 s41, s41, 0
	s_waitcnt vmcnt(16)
	v_pk_fma_f32 v[128:129], v[128:129], v[234:235], v[178:179]
	v_pk_fma_f32 v[130:131], v[130:131], v[236:237], v[180:181]
	v_pk_fma_f32 v[132:133], v[132:133], v[238:239], v[182:183]
	v_pk_fma_f32 v[134:135], v[134:135], v[240:241], v[184:185]
	global_store_dwordx4 v139, v[128:131], s[42:43]
	global_store_dwordx4 v139, v[132:135], s[42:43] offset:16
	s_add_u32 s42, s42, 0x10000
	s_addc_u32 s43, s43, 0
	global_load_dwordx4 v[178:181], v139, s[40:41] offset:512
	global_load_dwordx4 v[182:185], v139, s[40:41] offset:528
	s_add_u32 s40, s40, 0x10000
	s_addc_u32 s41, s41, 0
	s_waitcnt vmcnt(18)
	v_pk_fma_f32 v[124:125], v[124:125], v[234:235], v[186:187]
	v_pk_fma_f32 v[126:127], v[126:127], v[236:237], v[188:189]
	v_pk_fma_f32 v[120:121], v[120:121], v[238:239], v[190:191]
	v_pk_fma_f32 v[122:123], v[122:123], v[240:241], v[192:193]
	global_store_dwordx4 v139, v[124:127], s[42:43]
	global_store_dwordx4 v139, v[120:123], s[42:43] offset:16
	s_add_u32 s42, s42, 0x10000
	s_addc_u32 s43, s43, 0
	global_load_dwordx4 v[186:189], v139, s[40:41] offset:512
	global_load_dwordx4 v[190:193], v139, s[40:41] offset:528
	s_add_u32 s40, s40, 0x10000
	s_addc_u32 s41, s41, 0
	s_waitcnt vmcnt(20)
	v_pk_fma_f32 v[112:113], v[112:113], v[234:235], v[194:195]
	v_pk_fma_f32 v[114:115], v[114:115], v[236:237], v[196:197]
	v_pk_fma_f32 v[116:117], v[116:117], v[238:239], v[198:199]
	v_pk_fma_f32 v[118:119], v[118:119], v[240:241], v[200:201]
	global_store_dwordx4 v139, v[112:115], s[42:43]
	global_store_dwordx4 v139, v[116:119], s[42:43] offset:16
	s_add_u32 s42, s42, 0x10000
	s_addc_u32 s43, s43, 0
	global_load_dwordx4 v[194:197], v139, s[40:41] offset:512
	global_load_dwordx4 v[198:201], v139, s[40:41] offset:528
	s_add_u32 s40, s40, 0x50000
	s_addc_u32 s41, s41, 0
	s_waitcnt vmcnt(22)
	v_pk_fma_f32 v[100:101], v[100:101], v[234:235], v[202:203]
	v_pk_fma_f32 v[102:103], v[102:103], v[236:237], v[204:205]
	v_pk_fma_f32 v[96:97], v[96:97], v[238:239], v[206:207]
	v_pk_fma_f32 v[98:99], v[98:99], v[240:241], v[208:209]
	global_store_dwordx4 v139, v[100:103], s[42:43]
	global_store_dwordx4 v139, v[96:99], s[42:43] offset:16
	s_add_u32 s42, s42, 0x50000
	s_addc_u32 s43, s43, 0
	global_load_dwordx4 v[202:205], v139, s[40:41] offset:512
	global_load_dwordx4 v[206:209], v139, s[40:41] offset:528
	s_add_u32 s40, s40, 0x10000
	s_addc_u32 s41, s41, 0
	s_waitcnt vmcnt(24)
	v_pk_fma_f32 v[104:105], v[104:105], v[234:235], v[210:211]
	v_pk_fma_f32 v[106:107], v[106:107], v[236:237], v[212:213]
	v_pk_fma_f32 v[108:109], v[108:109], v[238:239], v[214:215]
	v_pk_fma_f32 v[110:111], v[110:111], v[240:241], v[216:217]
	global_store_dwordx4 v139, v[104:107], s[42:43]
	global_store_dwordx4 v139, v[108:111], s[42:43] offset:16
	s_add_u32 s42, s42, 0x10000
	s_addc_u32 s43, s43, 0
	global_load_dwordx4 v[210:213], v139, s[40:41] offset:512
	global_load_dwordx4 v[214:217], v139, s[40:41] offset:528
	s_add_u32 s40, s40, 0x10000
	s_addc_u32 s41, s41, 0
	s_waitcnt vmcnt(26)
	v_pk_fma_f32 v[92:93], v[92:93], v[234:235], v[218:219]
	v_pk_fma_f32 v[94:95], v[94:95], v[236:237], v[220:221]
	v_pk_fma_f32 v[84:85], v[84:85], v[238:239], v[222:223]
	v_pk_fma_f32 v[86:87], v[86:87], v[240:241], v[224:225]
	global_store_dwordx4 v139, v[92:95], s[42:43]
	global_store_dwordx4 v139, v[84:87], s[42:43] offset:16
	s_add_u32 s42, s42, 0x10000
	s_addc_u32 s43, s43, 0
	global_load_dwordx4 v[218:221], v139, s[40:41] offset:512
	global_load_dwordx4 v[222:225], v139, s[40:41] offset:528
	s_add_u32 s40, s40, 0x10000
	s_addc_u32 s41, s41, 0
	s_waitcnt vmcnt(28)
	v_pk_fma_f32 v[72:73], v[72:73], v[234:235], v[226:227]
	v_pk_fma_f32 v[74:75], v[74:75], v[236:237], v[228:229]
	v_pk_fma_f32 v[76:77], v[76:77], v[238:239], v[230:231]
	v_pk_fma_f32 v[78:79], v[78:79], v[240:241], v[232:233]
	global_store_dwordx4 v139, v[72:75], s[42:43]
	global_store_dwordx4 v139, v[76:79], s[42:43] offset:16
	s_add_u32 s42, s42, 0x10000
	s_addc_u32 s43, s43, 0
	global_load_dwordx4 v[226:229], v139, s[40:41] offset:512
	global_load_dwordx4 v[230:233], v139, s[40:41] offset:528
	s_waitcnt vmcnt(30)
	v_pk_fma_f32 v[68:69], v[68:69], v[234:235], v[170:171]
	v_pk_fma_f32 v[70:71], v[70:71], v[236:237], v[172:173]
	v_pk_fma_f32 v[64:65], v[64:65], v[238:239], v[174:175]
	v_pk_fma_f32 v[66:67], v[66:67], v[240:241], v[176:177]
	global_store_dwordx4 v139, v[68:71], s[42:43]
	global_store_dwordx4 v139, v[64:67], s[42:43] offset:16
	s_mov_b64 s[42:43], s[46:47]
	s_waitcnt vmcnt(30)
	v_pk_fma_f32 v[56:57], v[56:57], v[242:243], v[150:151]
	v_pk_fma_f32 v[58:59], v[58:59], v[244:245], v[152:153]
	v_pk_fma_f32 v[60:61], v[60:61], v[246:247], v[162:163]
	v_pk_fma_f32 v[62:63], v[62:63], v[248:249], v[164:165]
	global_store_dwordx4 v139, v[56:59], s[42:43] offset:512
	global_store_dwordx4 v139, v[60:63], s[42:43] offset:528
	s_add_u32 s42, s42, 0x10000
	s_addc_u32 s43, s43, 0
	s_waitcnt vmcnt(28)
	v_pk_fma_f32 v[52:53], v[52:53], v[242:243], v[178:179]
	v_pk_fma_f32 v[54:55], v[54:55], v[244:245], v[180:181]
	v_pk_fma_f32 v[48:49], v[48:49], v[246:247], v[182:183]
	v_pk_fma_f32 v[50:51], v[50:51], v[248:249], v[184:185]
	global_store_dwordx4 v139, v[52:55], s[42:43] offset:512
	global_store_dwordx4 v139, v[48:51], s[42:43] offset:528
	s_add_u32 s42, s42, 0x10000
	s_addc_u32 s43, s43, 0
	s_waitcnt vmcnt(26)
	v_pk_fma_f32 v[40:41], v[40:41], v[242:243], v[186:187]
	v_pk_fma_f32 v[42:43], v[42:43], v[244:245], v[188:189]
	v_pk_fma_f32 v[44:45], v[44:45], v[246:247], v[190:191]
	v_pk_fma_f32 v[46:47], v[46:47], v[248:249], v[192:193]
	global_store_dwordx4 v139, v[40:43], s[42:43] offset:512
	global_store_dwordx4 v139, v[44:47], s[42:43] offset:528
	s_add_u32 s42, s42, 0x10000
	s_addc_u32 s43, s43, 0
	s_waitcnt vmcnt(24)
	v_pk_fma_f32 v[32:33], v[32:33], v[242:243], v[194:195]
	v_pk_fma_f32 v[34:35], v[34:35], v[244:245], v[196:197]
	v_pk_fma_f32 v[24:25], v[24:25], v[246:247], v[198:199]
	v_pk_fma_f32 v[26:27], v[26:27], v[248:249], v[200:201]
	global_store_dwordx4 v139, v[32:35], s[42:43] offset:512
	global_store_dwordx4 v139, v[24:27], s[42:43] offset:528
	s_add_u32 s42, s42, 0x50000
	s_addc_u32 s43, s43, 0
	s_waitcnt vmcnt(22)
	v_pk_fma_f32 v[36:37], v[36:37], v[242:243], v[202:203]
	v_pk_fma_f32 v[38:39], v[38:39], v[244:245], v[204:205]
	v_pk_fma_f32 v[28:29], v[28:29], v[246:247], v[206:207]
	v_pk_fma_f32 v[30:31], v[30:31], v[248:249], v[208:209]
	global_store_dwordx4 v139, v[36:39], s[42:43] offset:512
	global_store_dwordx4 v139, v[28:31], s[42:43] offset:528
	s_add_u32 s42, s42, 0x10000
	s_addc_u32 s43, s43, 0
	s_waitcnt vmcnt(20)
	v_pk_fma_f32 v[20:21], v[20:21], v[242:243], v[210:211]
	v_pk_fma_f32 v[22:23], v[22:23], v[244:245], v[212:213]
	v_pk_fma_f32 v[16:17], v[16:17], v[246:247], v[214:215]
	v_pk_fma_f32 v[18:19], v[18:19], v[248:249], v[216:217]
	global_store_dwordx4 v139, v[20:23], s[42:43] offset:512
	global_store_dwordx4 v139, v[16:19], s[42:43] offset:528
	s_add_u32 s42, s42, 0x10000
	s_addc_u32 s43, s43, 0
	s_waitcnt vmcnt(18)
	v_pk_fma_f32 v[12:13], v[12:13], v[242:243], v[218:219]
	v_pk_fma_f32 v[14:15], v[14:15], v[244:245], v[220:221]
	v_pk_fma_f32 v[8:9], v[8:9], v[246:247], v[222:223]
	v_pk_fma_f32 v[10:11], v[10:11], v[248:249], v[224:225]
	global_store_dwordx4 v139, v[12:15], s[42:43] offset:512
	global_store_dwordx4 v139, v[8:11], s[42:43] offset:528
	s_add_u32 s42, s42, 0x10000
	s_addc_u32 s43, s43, 0
	s_waitcnt vmcnt(16)
	v_pk_fma_f32 v[4:5], v[4:5], v[242:243], v[226:227]
	v_pk_fma_f32 v[6:7], v[6:7], v[244:245], v[228:229]
	v_pk_fma_f32 v[0:1], v[0:1], v[246:247], v[230:231]
	v_pk_fma_f32 v[2:3], v[2:3], v[248:249], v[232:233]
	global_store_dwordx4 v139, v[4:7], s[42:43] offset:512
	global_store_dwordx4 v139, v[0:3], s[42:43] offset:528
	v_pk_mul_f32 v[200:201], v[128:129], v[128:129]
	v_pk_mul_f32 v[202:203], v[124:125], v[124:125]
	v_pk_mul_f32 v[204:205], v[112:113], v[112:113]
	v_pk_mul_f32 v[206:207], v[100:101], v[100:101]
	v_pk_mul_f32 v[208:209], v[104:105], v[104:105]
	v_pk_mul_f32 v[210:211], v[92:93], v[92:93]
	v_pk_mul_f32 v[212:213], v[72:73], v[72:73]
	v_pk_mul_f32 v[214:215], v[68:69], v[68:69]
	v_pk_fma_f32 v[200:201], v[130:131], v[130:131], v[200:201]
	v_pk_fma_f32 v[202:203], v[126:127], v[126:127], v[202:203]
	v_pk_fma_f32 v[204:205], v[114:115], v[114:115], v[204:205]
	v_pk_fma_f32 v[206:207], v[102:103], v[102:103], v[206:207]
	v_pk_fma_f32 v[208:209], v[106:107], v[106:107], v[208:209]
	v_pk_fma_f32 v[210:211], v[94:95], v[94:95], v[210:211]
	v_pk_fma_f32 v[212:213], v[74:75], v[74:75], v[212:213]
	v_pk_fma_f32 v[214:215], v[70:71], v[70:71], v[214:215]
	v_pk_fma_f32 v[200:201], v[132:133], v[132:133], v[200:201]
	v_pk_fma_f32 v[202:203], v[120:121], v[120:121], v[202:203]
	v_pk_fma_f32 v[204:205], v[116:117], v[116:117], v[204:205]
	v_pk_fma_f32 v[206:207], v[96:97], v[96:97], v[206:207]
	v_pk_fma_f32 v[208:209], v[108:109], v[108:109], v[208:209]
	v_pk_fma_f32 v[210:211], v[84:85], v[84:85], v[210:211]
	v_pk_fma_f32 v[212:213], v[76:77], v[76:77], v[212:213]
	v_pk_fma_f32 v[214:215], v[64:65], v[64:65], v[214:215]
	v_pk_fma_f32 v[200:201], v[134:135], v[134:135], v[200:201]
	v_pk_fma_f32 v[202:203], v[122:123], v[122:123], v[202:203]
	v_pk_fma_f32 v[204:205], v[118:119], v[118:119], v[204:205]
	v_pk_fma_f32 v[206:207], v[98:99], v[98:99], v[206:207]
	v_pk_fma_f32 v[208:209], v[110:111], v[110:111], v[208:209]
	v_pk_fma_f32 v[210:211], v[86:87], v[86:87], v[210:211]
	v_pk_fma_f32 v[212:213], v[78:79], v[78:79], v[212:213]
	v_pk_fma_f32 v[214:215], v[66:67], v[66:67], v[214:215]
	v_pk_fma_f32 v[200:201], v[56:57], v[56:57], v[200:201]
	v_pk_fma_f32 v[202:203], v[52:53], v[52:53], v[202:203]
	v_pk_fma_f32 v[204:205], v[40:41], v[40:41], v[204:205]
	v_pk_fma_f32 v[206:207], v[32:33], v[32:33], v[206:207]
	v_pk_fma_f32 v[208:209], v[36:37], v[36:37], v[208:209]
	v_pk_fma_f32 v[210:211], v[20:21], v[20:21], v[210:211]
	v_pk_fma_f32 v[212:213], v[12:13], v[12:13], v[212:213]
	v_pk_fma_f32 v[214:215], v[4:5], v[4:5], v[214:215]
	v_pk_fma_f32 v[200:201], v[58:59], v[58:59], v[200:201]
	v_pk_fma_f32 v[202:203], v[54:55], v[54:55], v[202:203]
	v_pk_fma_f32 v[204:205], v[42:43], v[42:43], v[204:205]
	v_pk_fma_f32 v[206:207], v[34:35], v[34:35], v[206:207]
	v_pk_fma_f32 v[208:209], v[38:39], v[38:39], v[208:209]
	v_pk_fma_f32 v[210:211], v[22:23], v[22:23], v[210:211]
	v_pk_fma_f32 v[212:213], v[14:15], v[14:15], v[212:213]
	v_pk_fma_f32 v[214:215], v[6:7], v[6:7], v[214:215]
	v_pk_fma_f32 v[200:201], v[60:61], v[60:61], v[200:201]
	v_pk_fma_f32 v[202:203], v[48:49], v[48:49], v[202:203]
	v_pk_fma_f32 v[204:205], v[44:45], v[44:45], v[204:205]
	v_pk_fma_f32 v[206:207], v[24:25], v[24:25], v[206:207]
	v_pk_fma_f32 v[208:209], v[28:29], v[28:29], v[208:209]
	v_pk_fma_f32 v[210:211], v[16:17], v[16:17], v[210:211]
	v_pk_fma_f32 v[212:213], v[8:9], v[8:9], v[212:213]
	v_pk_fma_f32 v[214:215], v[0:1], v[0:1], v[214:215]
	v_pk_fma_f32 v[200:201], v[62:63], v[62:63], v[200:201]
	v_pk_fma_f32 v[202:203], v[50:51], v[50:51], v[202:203]
	v_pk_fma_f32 v[204:205], v[46:47], v[46:47], v[204:205]
	v_pk_fma_f32 v[206:207], v[26:27], v[26:27], v[206:207]
	v_pk_fma_f32 v[208:209], v[30:31], v[30:31], v[208:209]
	v_pk_fma_f32 v[210:211], v[18:19], v[18:19], v[210:211]
	v_pk_fma_f32 v[212:213], v[10:11], v[10:11], v[212:213]
	v_pk_fma_f32 v[214:215], v[2:3], v[2:3], v[214:215]
	v_add_f32_e32 v216, v200, v201
	v_add_f32_e32 v217, v202, v203
	v_add_f32_e32 v218, v204, v205
	v_add_f32_e32 v219, v206, v207
	v_add_f32_e32 v220, v208, v209
	v_add_f32_e32 v221, v210, v211
	v_add_f32_e32 v222, v212, v213
	v_add_f32_e32 v223, v214, v215
	v_and_b32_e32 v224, 63, v154
	v_xor_b32_e32 v225, 32, v224
	v_xor_b32_e32 v224, 16, v224
	v_lshlrev_b32_e32 v224, 2, v224
	v_lshlrev_b32_e32 v225, 2, v225
	ds_bpermute_b32 v226, v224, v216
	ds_bpermute_b32 v227, v224, v217
	ds_bpermute_b32 v228, v224, v218
	ds_bpermute_b32 v229, v224, v219
	ds_bpermute_b32 v230, v224, v220
	ds_bpermute_b32 v231, v224, v221
	ds_bpermute_b32 v232, v224, v222
	ds_bpermute_b32 v233, v224, v223
	s_waitcnt lgkmcnt(0)
	v_add_f32_e32 v216, v216, v226
	v_add_f32_e32 v217, v217, v227
	v_add_f32_e32 v218, v218, v228
	v_add_f32_e32 v219, v219, v229
	v_add_f32_e32 v220, v220, v230
	v_add_f32_e32 v221, v221, v231
	v_add_f32_e32 v222, v222, v232
	v_add_f32_e32 v223, v223, v233
	ds_bpermute_b32 v226, v225, v216
	ds_bpermute_b32 v227, v225, v217
	ds_bpermute_b32 v228, v225, v218
	ds_bpermute_b32 v229, v225, v219
	ds_bpermute_b32 v230, v225, v220
	ds_bpermute_b32 v231, v225, v221
	ds_bpermute_b32 v232, v225, v222
	ds_bpermute_b32 v233, v225, v223
	s_waitcnt lgkmcnt(0)
	v_add_f32_e32 v216, v216, v226
	v_add_f32_e32 v217, v217, v227
	v_add_f32_e32 v218, v218, v228
	v_add_f32_e32 v219, v219, v229
	v_add_f32_e32 v220, v220, v230
	v_add_f32_e32 v221, v221, v231
	v_add_f32_e32 v222, v222, v232
	v_add_f32_e32 v223, v223, v233
	v_bfe_u32 v234, v154, 6, 2
	v_lshlrev_b32_e32 v234, 8, v234
	v_lshrrev_b32_e32 v235, 8, v154
	v_lshl_add_u32 v234, v235, 6, v234
	v_and_b32_e32 v235, 15, v154
	v_add_u32_e32 v234, v234, v235
	v_lshlrev_b32_e32 v234, 2, v234
	ds_write_b32 v234, v216 offset:0
	ds_write_b32 v234, v217 offset:64
	ds_write_b32 v234, v218 offset:128
	ds_write_b32 v234, v219 offset:192
	ds_write_b32 v234, v220 offset:512
	ds_write_b32 v234, v221 offset:576
	ds_write_b32 v234, v222 offset:640
	ds_write_b32 v234, v223 offset:704
	s_waitcnt lgkmcnt(0)
	s_barrier
	v_cmp_gt_u32_e32 vcc, 0x100, v154
	s_and_saveexec_b64 s[48:49], vcc
	v_lshlrev_b32_e32 v235, 2, v154
	ds_read_b32 v236, v235
	ds_read_b32 v237, v235 offset:1024
	ds_read_b32 v238, v235 offset:2048
	ds_read_b32 v239, v235 offset:3072
	s_lshl_b32 s50, s8, 3
	s_and_b32 s50, s50, 56
	s_bfe_u32 s51, s8, 0x30003
	s_or_b32 s50, s50, s51
	s_lshl_b32 s50, s50, 2
	s_lshr_b32 s51, s8, 6
	s_or_b32 s50, s50, s51
	s_lshl_b32 s50, s50, 10
	s_add_u32 s50, s50, s72
	s_addc_u32 s51, s73, 0
	s_add_u32 s50, s50, 0x19500000
	s_addc_u32 s51, s51, 0
	s_waitcnt lgkmcnt(0)
	v_add_f32_e32 v236, v236, v237
	v_add_f32_e32 v238, v238, v239
	v_add_f32_e32 v236, v236, v238
	global_store_dword v235, v236, s[50:51]
	s_mov_b64 exec, s[48:49]
	s_mov_b32 s92, s8
	v_mov_b64_e32 v[242:243], v[0:1]
	v_mov_b64_e32 v[244:245], v[2:3]
	v_mov_b64_e32 v[246:247], v[4:5]
	v_mov_b64_e32 v[248:249], v[6:7]
	s_add_i32 s8, s8, s74
	s_add_i32 s13, s13, s20
	s_cmpk_lt_i32 s8, 0x100
	s_cbranch_scc0 .LBB0_594

.LBB0_698:
	s_or_b64 exec, exec, s[0:1]
	v_mov_b32_e32 v80, v154
	s_lshr_b32 s1, s10, 3
	v_and_b32_e32 v136, 15, v80
	v_lshrrev_b32_e32 v81, 1, v80
	v_ashrrev_i32_e32 v80, 2, v80
	s_lshl_b32 s0, s12, 8
	s_mul_i32 s1, s1, 0x9000
	v_and_b32_e32 v152, 0xffffffc0, v80
	v_and_b32_e32 v81, 0x78, v81
	s_add_u32 s10, s7, s1
	v_ashrrev_i32_e32 v153, 31, v152
	s_mov_b32 s1, s52
	v_lshl_or_b32 v144, s11, 8, v81
	v_lshl_add_u64 v[140:141], v[152:153], 0, s[0:1]
	v_ashrrev_i32_e32 v145, 31, v144
	v_or_b32_e32 v140, v140, v136
	s_addc_u32 s11, s8, 0
	v_lshlrev_b64 v[150:151], 2, v[144:145]
	v_lshlrev_b64 v[140:141], 12, v[140:141]
	v_lshl_add_u64 v[148:149], s[10:11], 0, v[150:151]
	v_lshl_add_u64 v[170:171], s[70:71], 0, v[140:141]
	v_lshl_add_u64 v[146:147], v[170:171], 0, v[150:151]
	s_nop 1
	v_readfirstlane_b32 s38, v146
	v_readfirstlane_b32 s39, v147
	s_nop 1
	v_subrev_u32_e32 v139, s38, v146
	s_mov_b64 s[40:41], s[38:39]
	s_mov_b64 s[42:43], s[38:39]
	s_mov_b64 s[44:45], s[40:41]
	s_mov_b64 s[46:47], s[42:43]
	global_load_dwordx4 v[234:237], v[148:149], off
	global_load_dwordx4 v[238:241], v[148:149], off offset:16
	global_load_dwordx4 v[242:245], v[148:149], off offset:512
	global_load_dwordx4 v[246:249], v[148:149], off offset:528
	global_load_dwordx4 v[178:181], v139, s[40:41]
	global_load_dwordx4 v[182:185], v139, s[40:41] offset:16
	s_add_u32 s40, s40, 0x10000
	s_addc_u32 s41, s41, 0
	global_load_dwordx4 v[186:189], v139, s[40:41]
	global_load_dwordx4 v[190:193], v139, s[40:41] offset:16
	s_add_u32 s40, s40, 0x10000
	s_addc_u32 s41, s41, 0
	global_load_dwordx4 v[194:197], v139, s[40:41]
	global_load_dwordx4 v[198:201], v139, s[40:41] offset:16
	s_add_u32 s40, s40, 0x10000
	s_addc_u32 s41, s41, 0
	global_load_dwordx4 v[202:205], v139, s[40:41]
	global_load_dwordx4 v[206:209], v139, s[40:41] offset:16
	s_add_u32 s40, s40, 0x50000
	s_addc_u32 s41, s41, 0
	global_load_dwordx4 v[210:213], v139, s[40:41]
	global_load_dwordx4 v[214:217], v139, s[40:41] offset:16
	s_add_u32 s40, s40, 0x10000
	s_addc_u32 s41, s41, 0
	global_load_dwordx4 v[218:221], v139, s[40:41]
	global_load_dwordx4 v[222:225], v139, s[40:41] offset:16
	s_add_u32 s40, s40, 0x10000
	s_addc_u32 s41, s41, 0
	global_load_dwordx4 v[226:229], v139, s[40:41]
	global_load_dwordx4 v[230:233], v139, s[40:41] offset:16
	s_add_u32 s40, s40, 0x10000
	s_addc_u32 s41, s41, 0
	global_load_dwordx4 v[170:173], v139, s[40:41]
	global_load_dwordx4 v[174:177], v139, s[40:41] offset:16
	s_mov_b64 s[40:41], s[44:45]
	global_load_dwordx4 v[150:153], v139, s[40:41] offset:512
	global_load_dwordx4 v[162:165], v139, s[40:41] offset:528
	s_add_u32 s40, s40, 0x10000
	s_addc_u32 s41, s41, 0
	s_waitcnt vmcnt(16)
	v_pk_mul_f32 v[132:133], v[132:133], v[234:235]
	v_pk_mul_f32 v[134:135], v[134:135], v[236:237]
	v_pk_mul_f32 v[128:129], v[128:129], v[238:239]
	v_pk_mul_f32 v[130:131], v[130:131], v[240:241]
	v_pk_fma_f32 v[132:133], v[132:133], 0.5, v[178:179] op_sel_hi:[1,0,1]
	v_pk_fma_f32 v[134:135], v[134:135], 0.5, v[180:181] op_sel_hi:[1,0,1]
	v_pk_fma_f32 v[128:129], v[128:129], 0.5, v[182:183] op_sel_hi:[1,0,1]
	v_pk_fma_f32 v[130:131], v[130:131], 0.5, v[184:185] op_sel_hi:[1,0,1]
	global_store_dwordx4 v139, v[132:135], s[42:43]
	global_store_dwordx4 v139, v[128:131], s[42:43] offset:16
	s_add_u32 s42, s42, 0x10000
	s_addc_u32 s43, s43, 0
	global_load_dwordx4 v[178:181], v139, s[40:41] offset:512
	global_load_dwordx4 v[182:185], v139, s[40:41] offset:528
	s_add_u32 s40, s40, 0x10000
	s_addc_u32 s41, s41, 0
	s_waitcnt vmcnt(18)
	v_pk_mul_f32 v[124:125], v[124:125], v[234:235]
	v_pk_mul_f32 v[126:127], v[126:127], v[236:237]
	v_pk_mul_f32 v[120:121], v[120:121], v[238:239]
	v_pk_mul_f32 v[122:123], v[122:123], v[240:241]
	v_pk_fma_f32 v[124:125], v[124:125], 0.5, v[186:187] op_sel_hi:[1,0,1]
	v_pk_fma_f32 v[126:127], v[126:127], 0.5, v[188:189] op_sel_hi:[1,0,1]
	v_pk_fma_f32 v[120:121], v[120:121], 0.5, v[190:191] op_sel_hi:[1,0,1]
	v_pk_fma_f32 v[122:123], v[122:123], 0.5, v[192:193] op_sel_hi:[1,0,1]
	global_store_dwordx4 v139, v[124:127], s[42:43]
	global_store_dwordx4 v139, v[120:123], s[42:43] offset:16
	s_add_u32 s42, s42, 0x10000
	s_addc_u32 s43, s43, 0
	global_load_dwordx4 v[186:189], v139, s[40:41] offset:512
	global_load_dwordx4 v[190:193], v139, s[40:41] offset:528
	s_add_u32 s40, s40, 0x10000
	s_addc_u32 s41, s41, 0
	s_waitcnt vmcnt(20)
	v_pk_mul_f32 v[116:117], v[116:117], v[234:235]
	v_pk_mul_f32 v[118:119], v[118:119], v[236:237]
	v_pk_mul_f32 v[112:113], v[112:113], v[238:239]
	v_pk_mul_f32 v[114:115], v[114:115], v[240:241]
	v_pk_fma_f32 v[116:117], v[116:117], 0.5, v[194:195] op_sel_hi:[1,0,1]
	v_pk_fma_f32 v[118:119], v[118:119], 0.5, v[196:197] op_sel_hi:[1,0,1]
	v_pk_fma_f32 v[112:113], v[112:113], 0.5, v[198:199] op_sel_hi:[1,0,1]
	v_pk_fma_f32 v[114:115], v[114:115], 0.5, v[200:201] op_sel_hi:[1,0,1]
	global_store_dwordx4 v139, v[116:119], s[42:43]
	global_store_dwordx4 v139, v[112:115], s[42:43] offset:16
	s_add_u32 s42, s42, 0x10000
	s_addc_u32 s43, s43, 0
	global_load_dwordx4 v[194:197], v139, s[40:41] offset:512
	global_load_dwordx4 v[198:201], v139, s[40:41] offset:528
	s_add_u32 s40, s40, 0x50000
	s_addc_u32 s41, s41, 0
	s_waitcnt vmcnt(22)
	v_pk_mul_f32 v[108:109], v[108:109], v[234:235]
	v_pk_mul_f32 v[110:111], v[110:111], v[236:237]
	v_pk_mul_f32 v[104:105], v[104:105], v[238:239]
	v_pk_mul_f32 v[106:107], v[106:107], v[240:241]
	v_pk_fma_f32 v[108:109], v[108:109], 0.5, v[202:203] op_sel_hi:[1,0,1]
	v_pk_fma_f32 v[110:111], v[110:111], 0.5, v[204:205] op_sel_hi:[1,0,1]
	v_pk_fma_f32 v[104:105], v[104:105], 0.5, v[206:207] op_sel_hi:[1,0,1]
	v_pk_fma_f32 v[106:107], v[106:107], 0.5, v[208:209] op_sel_hi:[1,0,1]
	global_store_dwordx4 v139, v[108:111], s[42:43]
	global_store_dwordx4 v139, v[104:107], s[42:43] offset:16
	s_add_u32 s42, s42, 0x50000
	s_addc_u32 s43, s43, 0
	global_load_dwordx4 v[202:205], v139, s[40:41] offset:512
	global_load_dwordx4 v[206:209], v139, s[40:41] offset:528
	s_add_u32 s40, s40, 0x10000
	s_addc_u32 s41, s41, 0
	s_waitcnt vmcnt(24)
	v_pk_mul_f32 v[100:101], v[100:101], v[234:235]
	v_pk_mul_f32 v[102:103], v[102:103], v[236:237]
	v_pk_mul_f32 v[96:97], v[96:97], v[238:239]
	v_pk_mul_f32 v[98:99], v[98:99], v[240:241]
	v_pk_fma_f32 v[100:101], v[100:101], 0.5, v[210:211] op_sel_hi:[1,0,1]
	v_pk_fma_f32 v[102:103], v[102:103], 0.5, v[212:213] op_sel_hi:[1,0,1]
	v_pk_fma_f32 v[96:97], v[96:97], 0.5, v[214:215] op_sel_hi:[1,0,1]
	v_pk_fma_f32 v[98:99], v[98:99], 0.5, v[216:217] op_sel_hi:[1,0,1]
	global_store_dwordx4 v139, v[100:103], s[42:43]
	global_store_dwordx4 v139, v[96:99], s[42:43] offset:16
	s_add_u32 s42, s42, 0x10000
	s_addc_u32 s43, s43, 0
	global_load_dwordx4 v[210:213], v139, s[40:41] offset:512
	global_load_dwordx4 v[214:217], v139, s[40:41] offset:528
	s_add_u32 s40, s40, 0x10000
	s_addc_u32 s41, s41, 0
	s_waitcnt vmcnt(26)
	v_pk_mul_f32 v[92:93], v[92:93], v[234:235]
	v_pk_mul_f32 v[94:95], v[94:95], v[236:237]
	v_pk_mul_f32 v[88:89], v[88:89], v[238:239]
	v_pk_mul_f32 v[90:91], v[90:91], v[240:241]
	v_pk_fma_f32 v[92:93], v[92:93], 0.5, v[218:219] op_sel_hi:[1,0,1]
	v_pk_fma_f32 v[94:95], v[94:95], 0.5, v[220:221] op_sel_hi:[1,0,1]
	v_pk_fma_f32 v[88:89], v[88:89], 0.5, v[222:223] op_sel_hi:[1,0,1]
	v_pk_fma_f32 v[90:91], v[90:91], 0.5, v[224:225] op_sel_hi:[1,0,1]
	global_store_dwordx4 v139, v[92:95], s[42:43]
	global_store_dwordx4 v139, v[88:91], s[42:43] offset:16
	s_add_u32 s42, s42, 0x10000
	s_addc_u32 s43, s43, 0
	global_load_dwordx4 v[218:221], v139, s[40:41] offset:512
	global_load_dwordx4 v[222:225], v139, s[40:41] offset:528
	s_add_u32 s40, s40, 0x10000
	s_addc_u32 s41, s41, 0
	s_waitcnt vmcnt(28)
	v_pk_mul_f32 v[76:77], v[76:77], v[234:235]
	v_pk_mul_f32 v[78:79], v[78:79], v[236:237]
	v_pk_mul_f32 v[72:73], v[72:73], v[238:239]
	v_pk_mul_f32 v[74:75], v[74:75], v[240:241]
	v_pk_fma_f32 v[76:77], v[76:77], 0.5, v[226:227] op_sel_hi:[1,0,1]
	v_pk_fma_f32 v[78:79], v[78:79], 0.5, v[228:229] op_sel_hi:[1,0,1]
	v_pk_fma_f32 v[72:73], v[72:73], 0.5, v[230:231] op_sel_hi:[1,0,1]
	v_pk_fma_f32 v[74:75], v[74:75], 0.5, v[232:233] op_sel_hi:[1,0,1]
	global_store_dwordx4 v139, v[76:79], s[42:43]
	global_store_dwordx4 v139, v[72:75], s[42:43] offset:16
	s_add_u32 s42, s42, 0x10000
	s_addc_u32 s43, s43, 0
	global_load_dwordx4 v[226:229], v139, s[40:41] offset:512
	global_load_dwordx4 v[230:233], v139, s[40:41] offset:528
	s_waitcnt vmcnt(30)
	v_pk_mul_f32 v[68:69], v[68:69], v[234:235]
	v_pk_mul_f32 v[70:71], v[70:71], v[236:237]
	v_pk_mul_f32 v[64:65], v[64:65], v[238:239]
	v_pk_mul_f32 v[66:67], v[66:67], v[240:241]
	v_pk_fma_f32 v[68:69], v[68:69], 0.5, v[170:171] op_sel_hi:[1,0,1]
	v_pk_fma_f32 v[70:71], v[70:71], 0.5, v[172:173] op_sel_hi:[1,0,1]
	v_pk_fma_f32 v[64:65], v[64:65], 0.5, v[174:175] op_sel_hi:[1,0,1]
	v_pk_fma_f32 v[66:67], v[66:67], 0.5, v[176:177] op_sel_hi:[1,0,1]
	global_store_dwordx4 v139, v[68:71], s[42:43]
	global_store_dwordx4 v139, v[64:67], s[42:43] offset:16
	s_mov_b64 s[42:43], s[46:47]
	s_waitcnt vmcnt(30)
	v_pk_mul_f32 v[60:61], v[60:61], v[242:243]
	v_pk_mul_f32 v[62:63], v[62:63], v[244:245]
	v_pk_mul_f32 v[56:57], v[56:57], v[246:247]
	v_pk_mul_f32 v[58:59], v[58:59], v[248:249]
	v_pk_fma_f32 v[60:61], v[60:61], 0.5, v[150:151] op_sel_hi:[1,0,1]
	v_pk_fma_f32 v[62:63], v[62:63], 0.5, v[152:153] op_sel_hi:[1,0,1]
	v_pk_fma_f32 v[56:57], v[56:57], 0.5, v[162:163] op_sel_hi:[1,0,1]
	v_pk_fma_f32 v[58:59], v[58:59], 0.5, v[164:165] op_sel_hi:[1,0,1]
	global_store_dwordx4 v139, v[60:63], s[42:43] offset:512
	global_store_dwordx4 v139, v[56:59], s[42:43] offset:528
	s_add_u32 s42, s42, 0x10000
	s_addc_u32 s43, s43, 0
	s_waitcnt vmcnt(28)
	v_pk_mul_f32 v[52:53], v[52:53], v[242:243]
	v_pk_mul_f32 v[54:55], v[54:55], v[244:245]
	v_pk_mul_f32 v[48:49], v[48:49], v[246:247]
	v_pk_mul_f32 v[50:51], v[50:51], v[248:249]
	v_pk_fma_f32 v[52:53], v[52:53], 0.5, v[178:179] op_sel_hi:[1,0,1]
	v_pk_fma_f32 v[54:55], v[54:55], 0.5, v[180:181] op_sel_hi:[1,0,1]
	v_pk_fma_f32 v[48:49], v[48:49], 0.5, v[182:183] op_sel_hi:[1,0,1]
	v_pk_fma_f32 v[50:51], v[50:51], 0.5, v[184:185] op_sel_hi:[1,0,1]
	global_store_dwordx4 v139, v[52:55], s[42:43] offset:512
	global_store_dwordx4 v139, v[48:51], s[42:43] offset:528
	s_add_u32 s42, s42, 0x10000
	s_addc_u32 s43, s43, 0
	s_waitcnt vmcnt(26)
	v_pk_mul_f32 v[44:45], v[44:45], v[242:243]
	v_pk_mul_f32 v[46:47], v[46:47], v[244:245]
	v_pk_mul_f32 v[40:41], v[40:41], v[246:247]
	v_pk_mul_f32 v[42:43], v[42:43], v[248:249]
	v_pk_fma_f32 v[44:45], v[44:45], 0.5, v[186:187] op_sel_hi:[1,0,1]
	v_pk_fma_f32 v[46:47], v[46:47], 0.5, v[188:189] op_sel_hi:[1,0,1]
	v_pk_fma_f32 v[40:41], v[40:41], 0.5, v[190:191] op_sel_hi:[1,0,1]
	v_pk_fma_f32 v[42:43], v[42:43], 0.5, v[192:193] op_sel_hi:[1,0,1]
	global_store_dwordx4 v139, v[44:47], s[42:43] offset:512
	global_store_dwordx4 v139, v[40:43], s[42:43] offset:528
	s_add_u32 s42, s42, 0x10000
	s_addc_u32 s43, s43, 0
	s_waitcnt vmcnt(24)
	v_pk_mul_f32 v[36:37], v[36:37], v[242:243]
	v_pk_mul_f32 v[38:39], v[38:39], v[244:245]
	v_pk_mul_f32 v[32:33], v[32:33], v[246:247]
	v_pk_mul_f32 v[34:35], v[34:35], v[248:249]
	v_pk_fma_f32 v[36:37], v[36:37], 0.5, v[194:195] op_sel_hi:[1,0,1]
	v_pk_fma_f32 v[38:39], v[38:39], 0.5, v[196:197] op_sel_hi:[1,0,1]
	v_pk_fma_f32 v[32:33], v[32:33], 0.5, v[198:199] op_sel_hi:[1,0,1]
	v_pk_fma_f32 v[34:35], v[34:35], 0.5, v[200:201] op_sel_hi:[1,0,1]
	global_store_dwordx4 v139, v[36:39], s[42:43] offset:512
	global_store_dwordx4 v139, v[32:35], s[42:43] offset:528
	s_add_u32 s42, s42, 0x50000
	s_addc_u32 s43, s43, 0
	s_waitcnt vmcnt(22)
	v_pk_mul_f32 v[28:29], v[28:29], v[242:243]
	v_pk_mul_f32 v[30:31], v[30:31], v[244:245]
	v_pk_mul_f32 v[24:25], v[24:25], v[246:247]
	v_pk_mul_f32 v[26:27], v[26:27], v[248:249]
	v_pk_fma_f32 v[28:29], v[28:29], 0.5, v[202:203] op_sel_hi:[1,0,1]
	v_pk_fma_f32 v[30:31], v[30:31], 0.5, v[204:205] op_sel_hi:[1,0,1]
	v_pk_fma_f32 v[24:25], v[24:25], 0.5, v[206:207] op_sel_hi:[1,0,1]
	v_pk_fma_f32 v[26:27], v[26:27], 0.5, v[208:209] op_sel_hi:[1,0,1]
	global_store_dwordx4 v139, v[28:31], s[42:43] offset:512
	global_store_dwordx4 v139, v[24:27], s[42:43] offset:528
	s_add_u32 s42, s42, 0x10000
	s_addc_u32 s43, s43, 0
	s_waitcnt vmcnt(20)
	v_pk_mul_f32 v[20:21], v[20:21], v[242:243]
	v_pk_mul_f32 v[22:23], v[22:23], v[244:245]
	v_pk_mul_f32 v[16:17], v[16:17], v[246:247]
	v_pk_mul_f32 v[18:19], v[18:19], v[248:249]
	v_pk_fma_f32 v[20:21], v[20:21], 0.5, v[210:211] op_sel_hi:[1,0,1]
	v_pk_fma_f32 v[22:23], v[22:23], 0.5, v[212:213] op_sel_hi:[1,0,1]
	v_pk_fma_f32 v[16:17], v[16:17], 0.5, v[214:215] op_sel_hi:[1,0,1]
	v_pk_fma_f32 v[18:19], v[18:19], 0.5, v[216:217] op_sel_hi:[1,0,1]
	global_store_dwordx4 v139, v[20:23], s[42:43] offset:512
	global_store_dwordx4 v139, v[16:19], s[42:43] offset:528
	s_add_u32 s42, s42, 0x10000
	s_addc_u32 s43, s43, 0
	s_waitcnt vmcnt(18)
	v_pk_mul_f32 v[12:13], v[12:13], v[242:243]
	v_pk_mul_f32 v[14:15], v[14:15], v[244:245]
	v_pk_mul_f32 v[8:9], v[8:9], v[246:247]
	v_pk_mul_f32 v[10:11], v[10:11], v[248:249]
	v_pk_fma_f32 v[12:13], v[12:13], 0.5, v[218:219] op_sel_hi:[1,0,1]
	v_pk_fma_f32 v[14:15], v[14:15], 0.5, v[220:221] op_sel_hi:[1,0,1]
	v_pk_fma_f32 v[8:9], v[8:9], 0.5, v[222:223] op_sel_hi:[1,0,1]
	v_pk_fma_f32 v[10:11], v[10:11], 0.5, v[224:225] op_sel_hi:[1,0,1]
	global_store_dwordx4 v139, v[12:15], s[42:43] offset:512
	global_store_dwordx4 v139, v[8:11], s[42:43] offset:528
	s_add_u32 s42, s42, 0x10000
	s_addc_u32 s43, s43, 0
	s_waitcnt vmcnt(16)
	v_pk_mul_f32 v[4:5], v[4:5], v[242:243]
	v_pk_mul_f32 v[6:7], v[6:7], v[244:245]
	v_pk_mul_f32 v[0:1], v[0:1], v[246:247]
	v_pk_mul_f32 v[2:3], v[2:3], v[248:249]
	v_pk_fma_f32 v[4:5], v[4:5], 0.5, v[226:227] op_sel_hi:[1,0,1]
	v_pk_fma_f32 v[6:7], v[6:7], 0.5, v[228:229] op_sel_hi:[1,0,1]
	v_pk_fma_f32 v[0:1], v[0:1], 0.5, v[230:231] op_sel_hi:[1,0,1]
	v_pk_fma_f32 v[2:3], v[2:3], 0.5, v[232:233] op_sel_hi:[1,0,1]
	global_store_dwordx4 v139, v[4:7], s[42:43] offset:512
	global_store_dwordx4 v139, v[0:3], s[42:43] offset:528
	v_pk_mul_f32 v[200:201], v[132:133], v[132:133]
	v_pk_mul_f32 v[202:203], v[124:125], v[124:125]
	v_pk_mul_f32 v[204:205], v[116:117], v[116:117]
	v_pk_mul_f32 v[206:207], v[108:109], v[108:109]
	v_pk_mul_f32 v[208:209], v[100:101], v[100:101]
	v_pk_mul_f32 v[210:211], v[92:93], v[92:93]
	v_pk_mul_f32 v[212:213], v[76:77], v[76:77]
	v_pk_mul_f32 v[214:215], v[68:69], v[68:69]
	v_pk_fma_f32 v[200:201], v[134:135], v[134:135], v[200:201]
	v_pk_fma_f32 v[202:203], v[126:127], v[126:127], v[202:203]
	v_pk_fma_f32 v[204:205], v[118:119], v[118:119], v[204:205]
	v_pk_fma_f32 v[206:207], v[110:111], v[110:111], v[206:207]
	v_pk_fma_f32 v[208:209], v[102:103], v[102:103], v[208:209]
	v_pk_fma_f32 v[210:211], v[94:95], v[94:95], v[210:211]
	v_pk_fma_f32 v[212:213], v[78:79], v[78:79], v[212:213]
	v_pk_fma_f32 v[214:215], v[70:71], v[70:71], v[214:215]
	v_pk_fma_f32 v[200:201], v[128:129], v[128:129], v[200:201]
	v_pk_fma_f32 v[202:203], v[120:121], v[120:121], v[202:203]
	v_pk_fma_f32 v[204:205], v[112:113], v[112:113], v[204:205]
	v_pk_fma_f32 v[206:207], v[104:105], v[104:105], v[206:207]
	v_pk_fma_f32 v[208:209], v[96:97], v[96:97], v[208:209]
	v_pk_fma_f32 v[210:211], v[88:89], v[88:89], v[210:211]
	v_pk_fma_f32 v[212:213], v[72:73], v[72:73], v[212:213]
	v_pk_fma_f32 v[214:215], v[64:65], v[64:65], v[214:215]
	v_pk_fma_f32 v[200:201], v[130:131], v[130:131], v[200:201]
	v_pk_fma_f32 v[202:203], v[122:123], v[122:123], v[202:203]
	v_pk_fma_f32 v[204:205], v[114:115], v[114:115], v[204:205]
	v_pk_fma_f32 v[206:207], v[106:107], v[106:107], v[206:207]
	v_pk_fma_f32 v[208:209], v[98:99], v[98:99], v[208:209]
	v_pk_fma_f32 v[210:211], v[90:91], v[90:91], v[210:211]
	v_pk_fma_f32 v[212:213], v[74:75], v[74:75], v[212:213]
	v_pk_fma_f32 v[214:215], v[66:67], v[66:67], v[214:215]
	v_pk_fma_f32 v[200:201], v[60:61], v[60:61], v[200:201]
	v_pk_fma_f32 v[202:203], v[52:53], v[52:53], v[202:203]
	v_pk_fma_f32 v[204:205], v[44:45], v[44:45], v[204:205]
	v_pk_fma_f32 v[206:207], v[36:37], v[36:37], v[206:207]
	v_pk_fma_f32 v[208:209], v[28:29], v[28:29], v[208:209]
	v_pk_fma_f32 v[210:211], v[20:21], v[20:21], v[210:211]
	v_pk_fma_f32 v[212:213], v[12:13], v[12:13], v[212:213]
	v_pk_fma_f32 v[214:215], v[4:5], v[4:5], v[214:215]
	v_pk_fma_f32 v[200:201], v[62:63], v[62:63], v[200:201]
	v_pk_fma_f32 v[202:203], v[54:55], v[54:55], v[202:203]
	v_pk_fma_f32 v[204:205], v[46:47], v[46:47], v[204:205]
	v_pk_fma_f32 v[206:207], v[38:39], v[38:39], v[206:207]
	v_pk_fma_f32 v[208:209], v[30:31], v[30:31], v[208:209]
	v_pk_fma_f32 v[210:211], v[22:23], v[22:23], v[210:211]
	v_pk_fma_f32 v[212:213], v[14:15], v[14:15], v[212:213]
	v_pk_fma_f32 v[214:215], v[6:7], v[6:7], v[214:215]
	v_pk_fma_f32 v[200:201], v[56:57], v[56:57], v[200:201]
	v_pk_fma_f32 v[202:203], v[48:49], v[48:49], v[202:203]
	v_pk_fma_f32 v[204:205], v[40:41], v[40:41], v[204:205]
	v_pk_fma_f32 v[206:207], v[32:33], v[32:33], v[206:207]
	v_pk_fma_f32 v[208:209], v[24:25], v[24:25], v[208:209]
	v_pk_fma_f32 v[210:211], v[16:17], v[16:17], v[210:211]
	v_pk_fma_f32 v[212:213], v[8:9], v[8:9], v[212:213]
	v_pk_fma_f32 v[214:215], v[0:1], v[0:1], v[214:215]
	v_pk_fma_f32 v[200:201], v[58:59], v[58:59], v[200:201]
	v_pk_fma_f32 v[202:203], v[50:51], v[50:51], v[202:203]
	v_pk_fma_f32 v[204:205], v[42:43], v[42:43], v[204:205]
	v_pk_fma_f32 v[206:207], v[34:35], v[34:35], v[206:207]
	v_pk_fma_f32 v[208:209], v[26:27], v[26:27], v[208:209]
	v_pk_fma_f32 v[210:211], v[18:19], v[18:19], v[210:211]
	v_pk_fma_f32 v[212:213], v[10:11], v[10:11], v[212:213]
	v_pk_fma_f32 v[214:215], v[2:3], v[2:3], v[214:215]
	v_add_f32_e32 v216, v200, v201
	v_add_f32_e32 v217, v202, v203
	v_add_f32_e32 v218, v204, v205
	v_add_f32_e32 v219, v206, v207
	v_add_f32_e32 v220, v208, v209
	v_add_f32_e32 v221, v210, v211
	v_add_f32_e32 v222, v212, v213
	v_add_f32_e32 v223, v214, v215
	v_and_b32_e32 v224, 63, v154
	v_xor_b32_e32 v225, 32, v224
	v_xor_b32_e32 v224, 16, v224
	v_lshlrev_b32_e32 v224, 2, v224
	v_lshlrev_b32_e32 v225, 2, v225
	ds_bpermute_b32 v226, v224, v216
	ds_bpermute_b32 v227, v224, v217
	ds_bpermute_b32 v228, v224, v218
	ds_bpermute_b32 v229, v224, v219
	ds_bpermute_b32 v230, v224, v220
	ds_bpermute_b32 v231, v224, v221
	ds_bpermute_b32 v232, v224, v222
	ds_bpermute_b32 v233, v224, v223
	s_waitcnt lgkmcnt(0)
	v_add_f32_e32 v216, v216, v226
	v_add_f32_e32 v217, v217, v227
	v_add_f32_e32 v218, v218, v228
	v_add_f32_e32 v219, v219, v229
	v_add_f32_e32 v220, v220, v230
	v_add_f32_e32 v221, v221, v231
	v_add_f32_e32 v222, v222, v232
	v_add_f32_e32 v223, v223, v233
	ds_bpermute_b32 v226, v225, v216
	ds_bpermute_b32 v227, v225, v217
	ds_bpermute_b32 v228, v225, v218
	ds_bpermute_b32 v229, v225, v219
	ds_bpermute_b32 v230, v225, v220
	ds_bpermute_b32 v231, v225, v221
	ds_bpermute_b32 v232, v225, v222
	ds_bpermute_b32 v233, v225, v223
	s_waitcnt lgkmcnt(0)
	v_add_f32_e32 v216, v216, v226
	v_add_f32_e32 v217, v217, v227
	v_add_f32_e32 v218, v218, v228
	v_add_f32_e32 v219, v219, v229
	v_add_f32_e32 v220, v220, v230
	v_add_f32_e32 v221, v221, v231
	v_add_f32_e32 v222, v222, v232
	v_add_f32_e32 v223, v223, v233
	v_bfe_u32 v234, v154, 6, 2
	v_lshlrev_b32_e32 v234, 8, v234
	v_lshrrev_b32_e32 v235, 8, v154
	v_lshl_add_u32 v234, v235, 6, v234
	v_and_b32_e32 v235, 15, v154
	v_add_u32_e32 v234, v234, v235
	v_lshlrev_b32_e32 v234, 2, v234
	ds_write_b32 v234, v216 offset:0
	ds_write_b32 v234, v217 offset:64
	ds_write_b32 v234, v218 offset:128
	ds_write_b32 v234, v219 offset:192
	ds_write_b32 v234, v220 offset:512
	ds_write_b32 v234, v221 offset:576
	ds_write_b32 v234, v222 offset:640
	ds_write_b32 v234, v223 offset:704
	s_waitcnt lgkmcnt(0)
	s_barrier
	v_cmp_gt_u32_e32 vcc, 0x100, v154
	s_and_saveexec_b64 s[48:49], vcc
	v_lshlrev_b32_e32 v235, 2, v154
	ds_read_b32 v236, v235
	ds_read_b32 v237, v235 offset:1024
	ds_read_b32 v238, v235 offset:2048
	ds_read_b32 v239, v235 offset:3072
	s_lshl_b32 s50, s4, 3
	s_and_b32 s50, s50, 56
	s_bfe_u32 s51, s4, 0x30003
	s_or_b32 s50, s50, s51
	s_lshl_b32 s50, s50, 2
	s_lshr_b32 s51, s4, 6
	s_or_b32 s50, s50, s51
	s_lshl_b32 s50, s50, 10
	s_add_u32 s50, s50, s72
	s_addc_u32 s51, s73, 0
	s_add_u32 s50, s50, 0x19500000
	s_addc_u32 s51, s51, 0
	s_waitcnt lgkmcnt(0)
	v_add_f32_e32 v236, v236, v237
	v_add_f32_e32 v238, v238, v239
	v_add_f32_e32 v236, v236, v238
	global_store_dword v235, v236, s[50:51]
	s_mov_b64 exec, s[48:49]
	s_mov_b32 s92, s4
	v_mov_b64_e32 v[242:243], v[0:1]
	v_mov_b64_e32 v[244:245], v[2:3]
	v_mov_b64_e32 v[246:247], v[4:5]
	v_mov_b64_e32 v[248:249], v[6:7]
	s_add_i32 s4, s4, s74
	s_add_i32 s9, s9, s20
	s_cmpk_lt_i32 s4, 0x100
	s_cbranch_scc0 .LBB0_705
